# leader L2 write-back skipped at the P5->P6 and P6->P7 seams when a run-time census shows every tile-group on one XCC (else original path)
# speedup vs baseline: 1.0211x; 1.0034x over previous
; #define LAS __attribute__((address_space(3)))
; __device__ __forceinline__ unsigned xb_add(unsigned* p, unsigned v) { return __hip_atomic_fetch_add(p, v, __ATOMIC_RELAXED, __HIP_MEMORY_SCOPE_AGENT); }
; __device__ __forceinline__ unsigned xb_xcc_id() { return (unsigned)__builtin_amdgcn_s_getreg((3 << 11) | 20) & 0xFu; }
; __device__ __forceinline__ XcdBarrier xcd_barrier_post(unsigned* bar, volatile LAS unsigned* st) {
;     XcdBarrier b; b.bar = bar; b.x = xb_xcc_id(); b.st = st;
;     if (threadIdx.x == 0) (void)xb_add(&bar[XB_XCNT(b.x)], 1u);
;     return b;
.LBB9_14:
	s_waitcnt lgkmcnt(0)
	s_barrier
	s_getreg_b32 s2, hwreg(HW_REG_XCC_ID, 0, 4)
	s_and_b32 s96, s2, 15
	v_cmp_eq_u32_e64 s[80:81], 0, v208
	s_and_saveexec_b64 s[2:3], s[80:81]
	s_cbranch_execz .LBB9_17
	s_mov_b64 s[4:5], exec
	v_mbcnt_lo_u32_b32 v1, s4, 0
	v_mbcnt_hi_u32_b32 v1, s5, v1
	v_cmp_eq_u32_e32 vcc, 0, v1
	s_and_b64 s[8:9], exec, vcc
	s_mov_b64 exec, s[8:9]
	s_cbranch_execz .LBB9_17
	s_lshl_b32 s8, s96, 8
	s_bcnt1_i32_b64 s4, s[4:5]
	v_mov_b32_e32 v1, s8
	v_mov_b32_e32 v2, s4
	global_atomic_add v1, v2, s[90:91] offset:1024
	s_nop 1
	s_add_i32 s98, s96, 1
	s_lshl_b32 s99, s97, 2
	s_add_i32 s99, s99, 0x3800
	v_mov_b32_e32 v1, s99
	v_mov_b32_e32 v2, s98
	global_store_dword v1, v2, s[90:91]

; __device__ __forceinline__ void mk_p1(const Ptrs& P, int wave, int lane, int bx, int G) {
;     const int gw = bx * NWAVES + wave, NGW = G * NWAVES;
;     const float* mod = (const float*)(P.ws + WS_MOD); bf16_t* H = (bf16_t*)(P.ws + WS_H);
;     f32x4 A[4], Bv[4];
;     for (int m0 = gw * 8; m0 < MTOK; m0 += NGW * 8) { const float* mb = mod + (size_t)(m0 >> 12) * NMOD; h_factors(P.n1g, mb, mb + DM, A, Bv, lane);
;         h_rows<4>(P.x + (size_t)m0 * DM, A, Bv, H + (size_t)m0 * DM, lane); h_rows<4>(P.x + (size_t)(m0 + 4) * DM, A, Bv, H + (size_t)(m0 + 4) * DM, lane); }
.LBB9_135:
	s_and_saveexec_b64 s[98:99], s[80:81]
	s_cbranch_execz .Lxchk_done
	v_mov_b32_e32 v1, s97
	v_and_b32_e32 v1, 63, v1
	v_lshlrev_b32_e32 v1, 2, v1
	v_add_u32_e32 v1, 0x3800, v1
	global_load_dword v2, v1, s[90:91] sc1
	global_load_dword v3, v1, s[90:91] offset:256 sc1
	global_load_dword v4, v1, s[90:91] offset:512 sc1
	global_load_dword v5, v1, s[90:91] offset:768 sc1
	s_waitcnt vmcnt(0)
	v_cmp_ne_u32_e32 vcc, v2, v3
	s_cbranch_vccnz .Lxchk_bad
	v_cmp_ne_u32_e32 vcc, v2, v4
	s_cbranch_vccnz .Lxchk_bad
	v_cmp_ne_u32_e32 vcc, v2, v5
	s_cbranch_vccnz .Lxchk_bad
	v_cmp_eq_u32_e32 vcc, 0, v2
	s_cbranch_vccz .Lxchk_done
.Lxchk_bad:
	v_mov_b32_e32 v1, 0x3c00
	v_mov_b32_e32 v2, 1
	global_atomic_add v1, v2, s[90:91]
.Lxchk_done:
	s_or_b64 exec, exec, s[98:99]
	s_cmp_lt_i32 s92, 2
	s_cselect_b64 s[2:3], -1, 0
	s_and_b64 s[0:1], s[2:3], s[0:1]
	s_andn2_b64 vcc, exec, s[0:1]
	s_cbranch_vccnz .LBB9_204
	s_lshl_b32 s0, s97, 3
	s_add_i32 s0, s50, s0
	s_cmpk_gt_i32 s0, 0x7ff
	v_lshlrev_b32_e32 v44, 4, v170
	v_lshlrev_b32_e32 v46, 3, v170
	s_cbranch_scc1 .LBB9_139
	v_mbcnt_lo_u32_b32 v0, -1, 0
	v_mbcnt_hi_u32_b32 v0, -1, v0
	v_and_b32_e32 v1, 64, v0
	v_add_u32_e32 v1, 64, v1
	v_xor_b32_e32 v2, 1, v0
	v_cmp_lt_i32_e32 vcc, v2, v1
	s_add_u32 s1, s90, 0x1f40000
	s_addc_u32 s2, s91, 0
	v_cndmask_b32_e32 v2, v0, v2, vcc
	v_lshlrev_b32_e32 v72, 2, v2
	v_xor_b32_e32 v2, 2, v0
	v_cmp_lt_i32_e32 vcc, v2, v1
	s_lshl_b32 s4, s0, 3
	v_readlane_b32 s44, v251, 0
	v_cndmask_b32_e32 v2, v0, v2, vcc
	v_lshlrev_b32_e32 v73, 2, v2
	v_xor_b32_e32 v2, 4, v0
	v_cmp_lt_i32_e32 vcc, v2, v1
	v_readlane_b32 s45, v251, 1
	s_ashr_i32 s5, s4, 31
	v_cndmask_b32_e32 v2, v0, v2, vcc
	v_lshlrev_b32_e32 v74, 2, v2
	v_xor_b32_e32 v2, 8, v0
	v_cmp_lt_i32_e32 vcc, v2, v1
	s_lshl_b32 s8, s94, 6
	s_mov_b64 s[16:17], s[44:45]
	v_cndmask_b32_e32 v2, v0, v2, vcc
	v_lshlrev_b32_e32 v75, 2, v2
	v_xor_b32_e32 v2, 16, v0
	v_cmp_lt_i32_e32 vcc, v2, v1
	s_lshl_b64 s[10:11], s[4:5], 12
	s_add_u32 s10, s16, s10
	v_cndmask_b32_e32 v2, v0, v2, vcc
	v_lshlrev_b32_e32 v76, 2, v2
	v_xor_b32_e32 v2, 32, v0
	v_cmp_lt_i32_e32 vcc, v2, v1
	v_mov_b32_e32 v45, 0
	s_addc_u32 s11, s17, s11
	v_cndmask_b32_e32 v0, v0, v2, vcc
	v_lshlrev_b32_e32 v77, 2, v0
	v_lshl_add_u64 v[0:1], s[10:11], 0, v[44:45]
	s_mov_b64 s[10:11], 0x4000
	s_ashr_i32 s9, s8, 31
	v_lshl_add_u64 v[50:51], v[0:1], 0, s[10:11]
	s_lshl_b64 s[10:11], s[8:9], 12
	s_lshl_b64 s[12:13], s[4:5], 11
	s_add_u32 s12, s90, s12
	v_readlane_b32 s56, v251, 12
	v_readlane_b32 s57, v251, 13
	v_mov_b32_e32 v47, v45
	s_addc_u32 s13, s91, s13
	v_readlane_b32 s50, v251, 6
	v_readlane_b32 s58, v251, 14
	v_readlane_b32 s59, v251, 15
	s_mov_b64 s[28:29], s[56:57]
	v_lshl_add_u64 v[0:1], s[12:13], 0, v[46:47]
	s_mov_b64 s[12:13], 0x2003e00
	v_readlane_b32 s50, v251, 32
	v_lshl_add_u64 v[48:49], s[28:29], 0, v[44:45]
	v_lshl_add_u64 v[52:53], v[0:1], 0, s[12:13]
	s_lshl_b64 s[12:13], s[8:9], 11
	v_lshlrev_b32_e32 v54, 4, v170
	v_mov_b32_e32 v55, v45
	s_mov_b64 s[16:17], 0x1000
	s_movk_i32 s3, 0x1000
	s_movk_i32 s5, 0xd000
	s_movk_i32 s9, 0xe000
	s_movk_i32 s18, 0xf000
	v_mov_b32_e32 v45, 0x358637bd
	s_movk_i32 s19, 0x2000
	s_movk_i32 s20, 0x3000
	v_readlane_b32 s46, v251, 2
	v_readlane_b32 s47, v251, 3
	v_readlane_b32 s48, v251, 4
	v_readlane_b32 s49, v251, 5
	v_readlane_b32 s51, v251, 7
	v_readlane_b32 s52, v251, 8
	v_readlane_b32 s53, v251, 9
	v_readlane_b32 s54, v251, 10
	v_readlane_b32 s55, v251, 11
	s_mov_b64 s[30:31], s[58:59]

; #define LAS __attribute__((address_space(3)))
; __device__ __forceinline__ void mk_p2(const Ptrs& P, LAS unsigned char* lds, int tid, int wave, int lane, int bx, int G, bool dry) {
;     unsigned char* ws = P.ws; (void)tid; (void)wave; (void)lane;
;     bf16_t *WIN = (bf16_t*)(ws + WS_WIN), *H = (bf16_t*)(ws + WS_H), *Q = (bf16_t*)(ws + WS_Q), *GATES = (bf16_t*)(ws + WS_GATES), *PG = (bf16_t*)(ws + WS_PG);
;     const float* MOD = (const float*)(ws + WS_MOD); float* SSQ = (float*)(ws + WS_SSQ); (void)WIN; (void)H; (void)Q; (void)GATES; (void)PG; (void)MOD; (void)SSQ;
;         EpiInRest rest{(bf16_t*)(ws + WS_VT), (bf16_t*)(ws + WS_POOLIN), GATES, P.gate_b}; EpiCtxV cv{(bf16_t*)(ws + WS_VCT)};
;         for (int t = bx; t < 256; t += G) ctx_tile(P, lds, t, tid, wave, lane);
.LBB9_204:
	s_and_saveexec_b64 s[98:99], s[80:81]
	s_cbranch_execz .Lxok_done
	v_mov_b32_e32 v1, 0x3c00
	global_load_dword v2, v1, s[90:91] sc1
	s_waitcnt vmcnt(0)
	v_cmp_eq_u32_e32 vcc, 0, v2
	s_nop 1
	v_cndmask_b32_e64 v2, 0, 1, vcc
	v_mov_b32_e32 v1, 0x24008
	ds_write_b32 v1, v2
	s_waitcnt lgkmcnt(0)
.Lxok_done:
	s_or_b64 exec, exec, s[98:99]
	s_and_b64 vcc, exec, s[6:7]
	s_cbranch_vccnz .LBB9_251
	s_cmpk_lt_i32 s97, 0x100
	s_cbranch_scc1 .LBB9_207
	v_lshrrev_b32_e32 v0, 5, v208
	v_and_b32_e32 v49, 4, v0
	v_lshlrev_b32_e32 v0, 2, v208
	v_lshlrev_b32_e32 v48, 4, v208
	v_lshrrev_b32_e32 v47, 2, v208
	v_bfe_u32 v44, v208, 4, 2
	v_and_b32_e32 v46, 32, v0
	v_lshlrev_b32_e32 v45, 1, v208
	s_cbranch_execz .LBB9_208
	s_branch .LBB9_215

; __device__ __forceinline__ unsigned xb_ld(unsigned* p)              { return __hip_atomic_load(p, __ATOMIC_RELAXED, __HIP_MEMORY_SCOPE_AGENT); }
; __device__ __forceinline__ unsigned xb_add(unsigned* p, unsigned v) { return __hip_atomic_fetch_add(p, v, __ATOMIC_RELAXED, __HIP_MEMORY_SCOPE_AGENT); }
; #define XB_SPIN(cond, bar) do { unsigned _sp = 0; while (cond) { __builtin_amdgcn_s_sleep(1); \
;     if ((++_sp & 255u) == 0u) { if (xb_ld(&(bar)[XB_TMO])) break; if (_sp > XB_SPIN_CAP) { atomicAdd(&(bar)[XB_TMO], 1u); break; } } } } while (0)
; __device__ __forceinline__ void xcd_barrier(const XcdBarrier& b) {
;     ...
;         if (old + 1u == (gen + 1u) * nloc) {
;             __builtin_amdgcn_fence(__ATOMIC_RELEASE, "agent");
;             asm volatile("s_waitcnt vmcnt(0)" ::: "memory");
;             const unsigned og = xb_add(&bar[XB_TOP], 1u);
;             const unsigned tg = og / nx;
;             if (og + 1u == (tg + 1u) * nx) xb_add(&bar[XB_TOPGEN], 1u);
;             else XB_SPIN(xb_ld(&bar[XB_TOPGEN]) == tg, bar);
;             __builtin_amdgcn_fence(__ATOMIC_ACQUIRE, "agent");
;             xb_add(&bar[XB_XGEN(b.x)], 1u);
;             asm volatile("s_waitcnt vmcnt(0)" ::: "memory");
.LBB9_739:
	s_andn2_saveexec_b64 s[2:3], s[8:9]
	s_cbranch_execz .LBB9_759
	s_mov_b64 s[2:3], exec
	v_mov_b32_e32 v1, 0x24008
	ds_read_b32 v1, v1
	s_waitcnt lgkmcnt(0)
	v_readfirstlane_b32 s98, v1
	s_nop 3
	s_cmp_eq_u32 s98, 1
	s_cbranch_scc1 .Lskipwb_3
	buffer_wbl2 sc1
.Lskipwb_3:
	buffer_inv sc1
	s_waitcnt lgkmcnt(0)
	s_waitcnt vmcnt(0)
	v_mbcnt_lo_u32_b32 v1, s2, 0
	v_mbcnt_hi_u32_b32 v1, s3, v1
	v_cmp_eq_u32_e32 vcc, 0, v1
	s_and_saveexec_b64 s[8:9], vcc
	s_cbranch_execz .LBB9_742
	s_bcnt1_i32_b64 s2, s[2:3]
	v_mov_b32_e32 v2, 0x3000
	v_mov_b32_e32 v3, s2
	global_atomic_add v2, v2, v3, s[90:91] offset:1024 sc0
